# workgroups idle in the last (quarter-occupied) round of MoE-down convert the next layer's first 384 fp8 weight items there; PREP of layers>=1 starts 384 items later
# speedup vs baseline: 1.0133x; 1.0037x over previous
; #define LAS __attribute__((address_space(3)))
; __device__ __forceinline__ unsigned xb_add(unsigned* p, unsigned v) { return __hip_atomic_fetch_add(p, v, __ATOMIC_RELAXED, __HIP_MEMORY_SCOPE_AGENT); }
; __device__ __forceinline__ unsigned xb_xcc_id() { return (unsigned)__builtin_amdgcn_s_getreg((3 << 11) | 20) & 0xFu; }
; #define GAS __attribute__((address_space(1)))
; __device__ __forceinline__ XcdBarrier xcd_barrier_post(unsigned* bar, volatile LAS unsigned* st, const bool is_t0) {
;     XcdBarrier b; b.bar = bar; b.x = xb_xcc_id(); b.st = st;
;     if (is_t0) (void)xb_add(&bar[XB_XCNT(b.x)], 1u);
;     return b;
; __global__ void __launch_bounds__(NTHR, 2) fwd(Args args) {
;     extern __shared__ __attribute__((aligned(16))) unsigned char lds_raw[];
;     Frame F;
;     F.lds = (LAS unsigned char*)lds_raw; F.ws = (GAS unsigned char*)args.ws; F.out = (GAS float*)args.out; F.in = args.in;
;     F.tid = threadIdx.x; F.lane = F.tid & 63; F.wave = __builtin_amdgcn_readfirstlane(F.tid >> 6); F.bid = blockIdx.x; F.G = gridDim.x;
;     const bool is_t0 = (F.tid == 0);
;     volatile LAS unsigned* MISC = (volatile LAS unsigned*)(F.lds + LDS_MISC);
;     if (F.tid < 128) MISC[F.tid] = 0u;
;     __syncthreads();
;     const int lo = args.ph_lo, hi = args.ph_hi;
;     const bool multi = (hi - lo) > 1;
;     XcdBarrier bar; bar.bar = (unsigned*)(F.ws + WS_CTL) + CW_BAR; bar.x = 0; bar.st = MISC + 8;
;     if (multi) bar = xcd_barrier_post((unsigned*)(F.ws + WS_CTL) + CW_BAR, MISC + 8, is_t0);
_Z3fwd4Args:
	s_mov_b32 s101, 0
	s_load_dwordx4 s[4:7], s[0:1], 0xa0
	s_load_dword s81, s[0:1], 0xb8
	s_mov_b32 s80, s2
	s_add_u32 s2, s0, 0xb8
	s_addc_u32 s3, s1, 0
	s_waitcnt lgkmcnt(0)
	v_writelane_b32 v251, s4, 0
	s_nop 1
	v_writelane_b32 v251, s5, 1
	v_writelane_b32 v251, s6, 2
	v_writelane_b32 v251, s7, 3
	v_writelane_b32 v251, s2, 4
	s_nop 1
	v_writelane_b32 v251, s3, 5
	s_movk_i32 s2, 0x80
	v_cmp_gt_u32_e32 vcc, s2, v0
	s_and_saveexec_b64 s[4:5], vcc
	v_lshl_add_u32 v1, v0, 2, 0
	v_add_u32_e32 v1, 0x20000, v1
	v_mov_b32_e32 v2, 0
	ds_write_b32 v1, v2
	s_or_b64 exec, exec, s[4:5]
	s_load_dwordx2 s[4:5], s[0:1], 0xb0
	v_cmp_eq_u32_e64 s[6:7], 0, v0
	s_mov_b32 s2, 0
	s_waitcnt lgkmcnt(0)
	v_writelane_b32 v251, s6, 6
	s_barrier
	s_nop 0
	v_writelane_b32 v251, s7, 7
	v_writelane_b32 v251, s4, 8
	s_sub_i32 s3, s5, s4
	s_cmp_lt_i32 s3, 2
	v_writelane_b32 v251, s5, 9
	s_cbranch_scc1 .LBB0_7
	s_getreg_b32 s2, hwreg(HW_REG_XCC_ID, 0, 4)
	s_and_b32 s2, s2, 15
	s_mov_b64 s[4:5], exec
	v_readlane_b32 s6, v251, 6
	v_readlane_b32 s7, v251, 7
	s_and_b64 s[6:7], s[4:5], s[6:7]
	s_mov_b64 exec, s[6:7]
	s_cbranch_execz .LBB0_6
	s_mov_b64 s[6:7], exec
	v_mbcnt_lo_u32_b32 v1, s6, 0
	v_mbcnt_hi_u32_b32 v1, s7, v1
	v_cmp_eq_u32_e32 vcc, 0, v1
	s_and_b64 s[8:9], exec, vcc
	s_mov_b64 exec, s[8:9]
	s_cbranch_execz .LBB0_6
	s_load_dwordx4 s[8:11], s[0:1], 0xa0
	s_lshl_b32 s3, s2, 8
	v_mov_b32_e32 v1, 0x4000
	s_waitcnt lgkmcnt(0)
	s_add_u32 s8, s10, s3
	s_addc_u32 s9, s11, 0
	s_bcnt1_i32_b64 s3, s[6:7]
	v_mov_b32_e32 v2, s3
	global_atomic_add v1, v2, s[8:9] offset:1024

; __device__ __forceinline__ float w_qscale(float wmax) { return exp2f(floorf(log2f(128.f / fmaxf(wmax, 1e-30f)))); }
; __device__ __forceinline__ bool witem_decode(const Frame& F, int l, int it, WItem& t) {
;     constexpr int I_GU = 4 * 16, I_DN = 4 * 8, N_GU = NE * I_GU, N_DN = NE * I_DN;
;     const float* wmax = (const float*)((const unsigned*)(F.ws + WS_CTL) + CW_WMAX);
;     int r = it, nblk, item;
;     if (r < N_GU) { const int le = l * NE + r / I_GU; t.W = F.in[16] + (size_t)le * D * 2048; t.WT = (unsigned char*)(F.ws + WS_WGU) + (size_t)le * 2048 * D; t.N = 2048; t.map = 1; nblk = 16; item = r % I_GU; t.scale = w_qscale(wmax[l * 2 + 0]); }
;     else if ((r -= N_GU) < N_DN) { const int le = l * NE + r / I_DN; t.W = F.in[18] + (size_t)le * FF * D; t.WT = (unsigned char*)(F.ws + WS_WDN) + (size_t)le * D * FF; t.N = D; t.map = 3; nblk = 8; item = r % I_DN; t.scale = w_qscale(wmax[l * 2 + 1]); }
;     else return false;
;     t.k0 = 256 * (item / nblk); t.n0 = 128 * (item % nblk); return true;
; }
; __device__ __forceinline__ void witem_load(const WItem& t, int wave, int lane, f32x4 (&v)[16]) {
;     const float* wp = t.W + (size_t)(t.k0 + 32 * wave + 16 * (lane >> 5)) * t.N + t.n0 + 4 * (lane & 31);
; #pragma unroll
;     for (int q = 0; q < 16; ++q) v[q] = __builtin_nontemporal_load((const f32x4*)(wp + (size_t)q * t.N));
; __device__ __forceinline__ void fp8_convert_range(const Frame& F, int l, int start, int stride, int limit) {
;     __syncthreads();
;     WItem ta, tb; f32x4 va[16], vb[16];
;     int it = start;
;     bool ha = it < limit && witem_decode(F, l, it, ta);
;     if (ha) witem_load(ta, F.wave, F.lane, va);
.LBB0_1345:
	s_movk_i32 s100, 0x600
	v_readlane_b32 s0, v250, 30
	v_readlane_b32 s1, v250, 31
	s_andn2_b64 vcc, exec, s[0:1]
	s_barrier
	s_cbranch_vccnz .LBB0_1354
.Lcvt_entry:
	s_lshl_b32 s4, s96, 5
	v_readlane_b32 s0, v250, 32
	s_cmp_lg_u32 s101, 0
	s_cbranch_scc1 .Lcv32_t
	s_cmp_lg_u32 s96, 0
	s_cselect_b32 s1, 6, 0
	s_add_i32 s0, s0, s1
	s_branch .Lcv32_e
.Lcv32_t:
	v_readlane_b32 s0, v248, 41
.Lcv32_e:
	s_add_i32 s0, s4, s0
	s_ashr_i32 s1, s0, 31
	s_lshl_b64 s[6:7], s[0:1], 23
	s_lshl_b64 s[10:11], s[0:1], 21
	s_lshl_b64 s[0:1], s[28:29], 2
	s_add_u32 s0, s78, s0
	s_addc_u32 s1, s79, s1
	global_load_dword v1, v224, s[0:1]
	s_add_u32 s0, s0, 0x2000
	v_readlane_b32 s40, v249, 8
	s_addc_u32 s1, s1, 0
	v_readlane_b32 s42, v249, 10
	v_readlane_b32 s43, v249, 11
	s_add_u32 s26, s42, s6
	s_mov_b32 s9, 0x43000000
	s_addc_u32 s27, s43, s7
	s_add_u32 s3, s78, 0x38000000
	s_addc_u32 s5, s79, 0
	s_add_u32 s14, s3, s10
	s_addc_u32 s15, s5, s11
	v_lshrrev_b32_e32 v2, 1, v0
	s_waitcnt vmcnt(6)
	v_and_b32_e32 v54, 16, v2
	v_readlane_b32 s44, v249, 12
	v_readlane_b32 s45, v249, 13
	v_readlane_b32 s44, v250, 35
	s_cmp_lg_u32 s101, 0
	s_cbranch_scc1 .Lcv35_t
	s_branch .Lcv35_e
.Lcv35_t:
	v_readlane_b32 s44, v248, 44
.Lcv35_e:
	s_waitcnt vmcnt(2)
	v_and_b32_e32 v130, 0x7c, v66
	v_readlane_b32 s45, v250, 36
	s_cmp_lg_u32 s101, 0
	s_cbranch_scc1 .Lcv36_t
	s_branch .Lcv36_e
.Lcv36_t:
	v_readlane_b32 s45, v248, 45
.Lcv36_e:
	v_lshlrev_b32_e32 v198, 2, v130
	v_ashrrev_i32_e32 v131, 4, v0
	v_add_u32_e32 v134, 32, v131
	v_add_u32_e32 v135, 64, v131
	v_add_u32_e32 v136, 0x60, v131
	v_lshrrev_b32_e32 v56, 2, v136
	v_and_b32_e32 v57, 0x63, v136
	s_waitcnt vmcnt(1)
	v_mov_b32_e32 v133, v199
	v_readlane_b32 s41, v249, 9
	v_readlane_b32 s46, v249, 14
	v_readlane_b32 s47, v249, 15
	s_waitcnt vmcnt(0)
	v_max_f32_e32 v1, v1, v1
	v_max_f32_e32 v1, 0xda24260, v1
	v_div_scale_f32 v3, s[6:7], v1, v1, s9
	v_rcp_f32_e32 v4, v3
	v_div_scale_f32 v5, vcc, s9, v1, s9
	s_mov_b32 s6, 0x800000
	v_fma_f32 v6, -v3, v4, 1.0
	v_fmac_f32_e32 v4, v6, v4
	v_mul_f32_e32 v6, v5, v4
	v_fma_f32 v7, -v3, v6, v5
	v_fmac_f32_e32 v6, v7, v4
	v_fma_f32 v3, -v3, v6, v5
	v_div_fmas_f32 v3, v3, v4, v6
	v_div_fixup_f32 v1, v3, v1, s9
	v_cmp_gt_f32_e32 vcc, s6, v1
	s_and_b64 s[6:7], vcc, exec
	s_cselect_b32 s6, 32, 0
	v_ldexp_f32 v1, v1, s6
	v_log_f32_e32 v1, v1
	v_cndmask_b32_e32 v3, 0, v232, vcc
	s_mov_b32 s6, 0xc2fc0000
	v_readlane_b32 s9, v250, 34
	s_cmp_lg_u32 s101, 0
	s_cbranch_scc1 .Lcv34_t
	s_branch .Lcv34_e
.Lcv34_t:
	v_readlane_b32 s9, v248, 43
.Lcv34_e:
	v_sub_f32_e32 v1, v1, v3
	v_floor_f32_e32 v1, v1
	v_cmp_gt_f32_e32 vcc, s6, v1
	s_and_b64 s[6:7], vcc, exec
	s_cselect_b32 s7, 0xffffffc0, 0
	s_lshl_b32 s6, s8, 5
	s_add_i32 s8, s6, s9
	v_or_b32_e32 v2, s8, v54
	v_ashrrev_i32_e32 v3, 31, v2
	v_lshlrev_b64 v[2:3], 13, v[2:3]
	v_lshl_add_u64 v[2:3], s[26:27], 0, v[2:3]
	v_lshl_add_u64 v[2:3], s[44:45], 2, v[2:3]
	v_lshl_add_u64 v[38:39], v[2:3], 0, v[198:199]
	v_cndmask_b32_e32 v55, 0, v233, vcc
	v_add_co_u32_e32 v6, vcc, s70, v38
	s_movk_i32 s8, 0x4000
	s_nop 0
	v_addc_co_u32_e32 v7, vcc, 0, v39, vcc
	v_add_co_u32_e32 v10, vcc, s8, v38
	s_movk_i32 s8, 0x6000
	s_nop 0
	v_addc_co_u32_e32 v11, vcc, 0, v39, vcc
	v_add_co_u32_e32 v14, vcc, s8, v38
	s_mov_b32 s8, 0x8000
	s_nop 0
	v_addc_co_u32_e32 v15, vcc, 0, v39, vcc
	v_add_co_u32_e32 v18, vcc, s8, v38
	s_mov_b32 s8, 0xa000
	s_nop 0
	v_addc_co_u32_e32 v19, vcc, 0, v39, vcc
	v_add_co_u32_e32 v22, vcc, s8, v38
	s_mov_b32 s8, 0xc000
	s_nop 0
	v_addc_co_u32_e32 v23, vcc, 0, v39, vcc
	v_add_co_u32_e32 v26, vcc, s8, v38
	s_mov_b32 s8, 0xe000
	s_nop 0
	v_addc_co_u32_e32 v27, vcc, 0, v39, vcc
	v_add_co_u32_e32 v30, vcc, s8, v38
	s_mov_b32 s8, 0x12000
	s_nop 0
	v_addc_co_u32_e32 v31, vcc, 0, v39, vcc
	v_add_co_u32_e32 v34, vcc, s71, v38
	v_add_f32_e32 v1, v1, v55
	s_nop 0
	v_addc_co_u32_e32 v35, vcc, 0, v39, vcc
	v_add_co_u32_e32 v40, vcc, s8, v38
	s_mov_b32 s8, 0x14000
	s_nop 0
	v_addc_co_u32_e32 v41, vcc, 0, v39, vcc
	v_add_co_u32_e32 v42, vcc, s8, v38
	s_mov_b32 s8, 0x16000
	s_nop 0
	v_addc_co_u32_e32 v43, vcc, 0, v39, vcc
	v_add_co_u32_e32 v44, vcc, s8, v38
	s_mov_b32 s8, 0x18000
	s_nop 0
	v_addc_co_u32_e32 v45, vcc, 0, v39, vcc
	v_add_co_u32_e32 v46, vcc, s8, v38
	s_mov_b32 s8, 0x1a000
	s_nop 0
	v_addc_co_u32_e32 v47, vcc, 0, v39, vcc
	v_add_co_u32_e32 v48, vcc, s8, v38
	s_mov_b32 s8, 0x1c000
	s_nop 0
	v_addc_co_u32_e32 v49, vcc, 0, v39, vcc
	global_load_dwordx4 v[2:5], v[38:39], off nt
	s_nop 0
	global_load_dwordx4 v[6:9], v[6:7], off nt
	s_nop 0
	global_load_dwordx4 v[10:13], v[10:11], off nt
	s_nop 0
	global_load_dwordx4 v[14:17], v[14:15], off nt
	s_nop 0
	global_load_dwordx4 v[18:21], v[18:19], off nt
	s_nop 0
	global_load_dwordx4 v[22:25], v[22:23], off nt
	s_nop 0
	global_load_dwordx4 v[26:29], v[26:27], off nt
	s_nop 0
	global_load_dwordx4 v[30:33], v[30:31], off nt
	s_nop 0
	global_load_dwordx4 v[34:37], v[34:35], off nt
	s_nop 0
	global_load_dwordx4 v[50:53], v[40:41], off nt
	global_load_dwordx4 v[62:65], v[42:43], off nt
	global_load_dwordx4 v[70:73], v[44:45], off nt
	global_load_dwordx4 v[82:85], v[46:47], off nt
	global_load_dwordx4 v[86:89], v[48:49], off nt
	v_add_co_u32_e32 v40, vcc, s8, v38
	s_mov_b32 s8, 0x1e000
	s_nop 0
	v_addc_co_u32_e32 v41, vcc, 0, v39, vcc
	v_add_co_u32_e32 v38, vcc, s8, v38
	v_exp_f32_e32 v1, v1
	s_nop 0
	v_addc_co_u32_e32 v39, vcc, 0, v39, vcc
	global_load_dwordx4 v[94:97], v[40:41], off nt
	global_load_dwordx4 v[102:105], v[38:39], off nt
	v_ldexp_f32 v146, v1, s7
	v_or_b32_e32 v1, s6, v54
	s_add_i32 s6, s6, 0
	v_and_b32_e32 v38, 31, v0
	v_mov_b32_e32 v39, s6
	s_movk_i32 s6, 0x110
	v_lshlrev_b32_e32 v40, 5, v131
	v_mad_u32_u24 v38, v38, s6, v39
	v_lshlrev_b32_e32 v39, 4, v0
	v_and_b32_e32 v40, 0x60, v40
	v_ashrrev_i32_e32 v41, 6, v0
	v_lshrrev_b32_e32 v45, 2, v134
	v_lshrrev_b32_e32 v48, 2, v135
	v_and_b32_e32 v132, 0xf0, v39
	v_add_u32_e32 v41, v40, v41
	v_lshlrev_b32_e32 v42, 2, v131
	v_lshrrev_b32_e32 v43, 1, v131
	v_add_u32_e32 v45, v40, v45
	v_lshlrev_b32_e32 v46, 2, v134
	v_add_u32_e32 v48, v40, v48
	v_lshlrev_b32_e32 v49, 2, v135
	v_add_u32_e32 v40, v40, v56
	v_lshlrev_b32_e32 v56, 2, v136
	v_add_u32_e32 v39, 0, v132
	v_mul_lo_u32 v41, v41, s6
	v_and_b32_e32 v42, 16, v42
	v_and_b32_e32 v43, 12, v43
	v_and_b32_e32 v44, 0x63, v131
	v_mul_lo_u32 v45, v45, s6
	v_and_b32_e32 v46, 16, v46
	v_and_b32_e32 v47, 0x63, v134
	v_mul_lo_u32 v48, v48, s6
	v_and_b32_e32 v49, 16, v49
	v_and_b32_e32 v55, 0x63, v135
	v_mul_lo_u32 v40, v40, s6
	v_and_b32_e32 v56, 16, v56
	v_or3_b32 v137, v42, v44, v43
	v_or3_b32 v138, v47, v46, v43
	v_or3_b32 v139, v55, v49, v43
	v_or3_b32 v140, v57, v56, v43
	v_add_u32_e32 v141, v38, v54
	v_add_u32_e32 v142, v39, v41
	v_add_u32_e32 v143, v39, v45
	v_add_u32_e32 v144, v39, v48
	v_add_u32_e32 v145, v39, v40
	v_readlane_b32 s6, v250, 33
	s_cmp_lg_u32 s101, 0
	s_cbranch_scc1 .Lcv33_t
	s_cmp_lg_u32 s96, 0
	s_cselect_b32 s7, 0x180, 0
	s_add_i32 s6, s6, s7
	s_branch .Lcv33_e
.Lcv33_t:
	v_readlane_b32 s6, v248, 42
.Lcv33_e:
	s_mov_b32 s42, s9
	s_branch .LBB0_1348

; __device__ __forceinline__ float w_qscale(float wmax) { return exp2f(floorf(log2f(128.f / fmaxf(wmax, 1e-30f)))); }
; __device__ __forceinline__ bool witem_decode(const Frame& F, int l, int it, WItem& t) {
;     constexpr int I_GU = 4 * 16, I_DN = 4 * 8, N_GU = NE * I_GU, N_DN = NE * I_DN;
;     const float* wmax = (const float*)((const unsigned*)(F.ws + WS_CTL) + CW_WMAX);
;     int r = it, nblk, item;
;     if (r < N_GU) { const int le = l * NE + r / I_GU; t.W = F.in[16] + (size_t)le * D * 2048; t.WT = (unsigned char*)(F.ws + WS_WGU) + (size_t)le * 2048 * D; t.N = 2048; t.map = 1; nblk = 16; item = r % I_GU; t.scale = w_qscale(wmax[l * 2 + 0]); }
;     else if ((r -= N_GU) < N_DN) { const int le = l * NE + r / I_DN; t.W = F.in[18] + (size_t)le * FF * D; t.WT = (unsigned char*)(F.ws + WS_WDN) + (size_t)le * D * FF; t.N = D; t.map = 3; nblk = 8; item = r % I_DN; t.scale = w_qscale(wmax[l * 2 + 1]); }
;     else return false;
;     t.k0 = 256 * (item / nblk); t.n0 = 128 * (item % nblk); return true;
; }
; __device__ __forceinline__ void witem_load(const WItem& t, int wave, int lane, f32x4 (&v)[16]) {
;     const float* wp = t.W + (size_t)(t.k0 + 32 * wave + 16 * (lane >> 5)) * t.N + t.n0 + 4 * (lane & 31);
; #pragma unroll
;     for (int q = 0; q < 16; ++q) v[q] = __builtin_nontemporal_load((const f32x4*)(wp + (size_t)q * t.N));
; __device__ __forceinline__ void fp8_convert_range(const Frame& F, int l, int start, int stride, int limit) {
;     ...
;     while (ha) {
;         const bool hb = it + stride < limit && witem_decode(F, l, it + stride, tb);
;         if (hb) witem_load(tb, F.wave, F.lane, vb);
.LBB0_1348:
	s_add_i32 s7, s74, s6
	s_cmp_lt_i32 s7, s100
	s_cselect_b64 s[26:27], -1, 0
	s_cmp_ge_i32 s7, s100
	s_cbranch_scc1 .LBB0_1350
	global_load_dword v38, v199, s[0:1]
	s_ashr_i32 s8, s7, 31
	s_lshr_b32 s8, s8, 26
	s_add_i32 s30, s7, s8
	s_ashr_i32 s8, s30, 6
	s_add_i32 s8, s8, s4
	s_ashr_i32 s9, s8, 31
	v_readlane_b32 s48, v249, 8
	s_lshl_b64 s[10:11], s[8:9], 23
	v_readlane_b32 s50, v249, 10
	v_readlane_b32 s51, v249, 11
	s_add_u32 s46, s50, s10
	s_addc_u32 s47, s51, s11
	s_lshl_b64 s[8:9], s[8:9], 21
	s_add_u32 s28, s3, s8
	s_addc_u32 s29, s5, s9
	s_and_b32 s8, s30, 0xffc0
	s_mov_b32 s10, 0x43000000
	s_sub_i32 s7, s7, s8
	v_lshlrev_b32_e32 v198, 2, v130
	v_readlane_b32 s49, v249, 9
	v_readlane_b32 s52, v249, 12
	v_readlane_b32 s53, v249, 13
	v_readlane_b32 s54, v249, 14
	v_readlane_b32 s55, v249, 15
	s_waitcnt vmcnt(0)
	v_max_f32_e32 v38, v38, v38
	v_max_f32_e32 v38, 0xda24260, v38
	v_div_scale_f32 v39, s[8:9], v38, v38, s10
	v_rcp_f32_e32 v40, v39
	s_mov_b32 s8, 0x800000
	v_fma_f32 v41, -v39, v40, 1.0
	v_fmac_f32_e32 v40, v41, v40
	v_div_scale_f32 v41, vcc, s10, v38, s10
	v_mul_f32_e32 v42, v41, v40
	v_fma_f32 v43, -v39, v42, v41
	v_fmac_f32_e32 v42, v43, v40
	v_fma_f32 v39, -v39, v42, v41
	v_div_fmas_f32 v39, v39, v40, v42
	v_div_fixup_f32 v38, v39, v38, s10
	v_cmp_gt_f32_e32 vcc, s8, v38
	s_and_b64 s[8:9], vcc, exec
	s_cselect_b32 s8, 32, 0
	v_ldexp_f32 v38, v38, s8
	v_log_f32_e32 v38, v38
	v_cndmask_b32_e32 v39, 0, v232, vcc
	s_mov_b32 s8, 0xc2fc0000
	v_sub_f32_e32 v38, v38, v39
	v_floor_f32_e32 v38, v38
	v_cmp_gt_f32_e32 vcc, s8, v38
	s_and_b64 s[8:9], vcc, exec
	s_cselect_b32 s8, 0xffffffc0, 0
	v_cndmask_b32_e32 v39, 0, v233, vcc
	v_add_f32_e32 v38, v38, v39
	v_exp_f32_e32 v38, v38
	s_nop 0
	v_ldexp_f32 v147, v38, s8
	s_bfe_i32 s8, s7, 0x80000
	s_bfe_u32 s8, s8, 0x4000b
	s_add_i32 s8, s7, s8
	s_bfe_i32 s9, s8, 0x80000
	s_sext_i32_i16 s9, s9
	s_lshl_b32 s9, s9, 4
	s_and_b32 s36, s9, 0xffffff00
	s_and_b32 s8, s8, 0xf0
	s_sub_i32 s7, s7, s8
	v_add_u32_e32 v38, s36, v1
	s_sext_i32_i8 s7, s7
	v_ashrrev_i32_e32 v39, 31, v38
	s_lshl_b32 s40, s7, 7
	v_lshlrev_b64 v[38:39], 13, v[38:39]
	v_lshl_add_u64 v[38:39], s[46:47], 0, v[38:39]
	s_ashr_i32 s41, s40, 31
	v_lshl_add_u64 v[38:39], s[40:41], 2, v[38:39]
	v_lshl_add_u64 v[126:127], v[38:39], 0, v[198:199]
	v_add_co_u32_e32 v42, vcc, s70, v126
	s_movk_i32 s7, 0x4000
	s_nop 0
	v_addc_co_u32_e32 v43, vcc, 0, v127, vcc
	v_add_co_u32_e32 v46, vcc, s7, v126
	s_movk_i32 s7, 0x6000
	s_nop 0
	v_addc_co_u32_e32 v47, vcc, 0, v127, vcc
	v_add_co_u32_e32 v54, vcc, s7, v126
	s_mov_b32 s7, 0x8000
	s_nop 0
	v_addc_co_u32_e32 v55, vcc, 0, v127, vcc
	v_add_co_u32_e32 v58, vcc, s7, v126
	s_mov_b32 s7, 0xa000
	s_nop 0
	v_addc_co_u32_e32 v59, vcc, 0, v127, vcc
	v_add_co_u32_e32 v66, vcc, s7, v126
	s_mov_b32 s7, 0xc000
	s_nop 0
	v_addc_co_u32_e32 v67, vcc, 0, v127, vcc
	v_add_co_u32_e32 v74, vcc, s7, v126
	s_mov_b32 s7, 0xe000
	s_nop 0
	v_addc_co_u32_e32 v75, vcc, 0, v127, vcc
	v_add_co_u32_e32 v78, vcc, s7, v126
	s_mov_b32 s7, 0x12000
	s_nop 0
	v_addc_co_u32_e32 v79, vcc, 0, v127, vcc
	v_add_co_u32_e32 v90, vcc, s71, v126
	global_load_dwordx4 v[38:41], v[126:127], off nt
	s_nop 0
	v_addc_co_u32_e32 v91, vcc, 0, v127, vcc
	v_add_co_u32_e32 v98, vcc, s7, v126
	s_mov_b32 s7, 0x14000
	s_nop 0
	v_addc_co_u32_e32 v99, vcc, 0, v127, vcc
	v_add_co_u32_e32 v106, vcc, s7, v126
	s_mov_b32 s7, 0x16000
	s_nop 0
	v_addc_co_u32_e32 v107, vcc, 0, v127, vcc
	v_add_co_u32_e32 v110, vcc, s7, v126
	global_load_dwordx4 v[42:45], v[42:43], off nt
	s_nop 0
	v_addc_co_u32_e32 v111, vcc, 0, v127, vcc
	v_add_co_u32_e32 v114, vcc, 0x18000, v126
	global_load_dwordx4 v[46:49], v[46:47], off nt
	s_nop 0
	v_addc_co_u32_e32 v115, vcc, 0, v127, vcc
	v_add_co_u32_e32 v118, vcc, 0x1a000, v126
	global_load_dwordx4 v[54:57], v[54:55], off nt
	s_nop 0
	v_addc_co_u32_e32 v119, vcc, 0, v127, vcc
	v_add_co_u32_e32 v122, vcc, 0x1c000, v126
	global_load_dwordx4 v[58:61], v[58:59], off nt
	s_nop 0
	v_addc_co_u32_e32 v123, vcc, 0, v127, vcc
	v_add_co_u32_e32 v126, vcc, 0x1e000, v126
	global_load_dwordx4 v[66:69], v[66:67], off nt
	s_nop 0
	v_addc_co_u32_e32 v127, vcc, 0, v127, vcc
	global_load_dwordx4 v[74:77], v[74:75], off nt
	s_nop 0
	global_load_dwordx4 v[78:81], v[78:79], off nt
	s_nop 0
	global_load_dwordx4 v[90:93], v[90:91], off nt
	s_nop 0
	global_load_dwordx4 v[98:101], v[98:99], off nt
	s_nop 0
	global_load_dwordx4 v[106:109], v[106:107], off nt
	s_nop 0
	global_load_dwordx4 v[110:113], v[110:111], off nt
	s_nop 0
	global_load_dwordx4 v[114:117], v[114:115], off nt
	s_nop 0
	global_load_dwordx4 v[118:121], v[118:119], off nt
	s_nop 0
	global_load_dwordx4 v[122:125], v[122:123], off nt
	s_nop 0
	global_load_dwordx4 v[126:129], v[126:127], off nt
; #define LAS __attribute__((address_space(3)))
; __device__ __forceinline__ int map_row_rt(int map, int n) { return map == 0 ? n : (map == 1 ? map_row<1>(n) : (map == 3 ? map_row<3>(n) : map_row<2>(n))); }
; __device__ __forceinline__ void witem_store(const Frame& F, const WItem& t, const f32x4 (&v)[16], LAS unsigned char* tile) {
;     const int i = F.lane & 31, hi = F.lane >> 5;
; #pragma unroll
;     for (int j = 0; j < 4; ++j) {
;         u32x4 o;
; #pragma unroll
;         for (int d = 0; d < 4; ++d) { int r = __builtin_amdgcn_cvt_pk_fp8_f32(v[4 * d][j] * t.scale, v[4 * d + 1][j] * t.scale, 0, false);
;             r = __builtin_amdgcn_cvt_pk_fp8_f32(v[4 * d + 2][j] * t.scale, v[4 * d + 3][j] * t.scale, r, true); o[d] = (unsigned)r; }
;         *(LAS u32x4*)(tile + (32 * j + i) * 272 + 32 * F.wave + 16 * hi) = o;
;     }
;     __syncthreads();
;     const int c = F.tid & 15;
; #pragma unroll
;     for (int pass = 0; pass < 4; ++pass) { const int n = (F.tid >> 4) + 32 * pass, rho = (n & 3) * 32 + (n >> 2);
;         const u32x4 o = *(const LAS u32x4*)(tile + rho * 272 + 16 * c);
;         *(u32x4*)(t.WT + (size_t)map_row_rt(t.map, t.n0 + n) * D + t.k0 + 16 * c) = o; }
.LBB0_1350:
	s_waitcnt vmcnt(15)
	v_mul_f32_e32 v149, v2, v146
	s_waitcnt vmcnt(14)
	v_mul_f32_e32 v150, v6, v146
	v_mov_b32_e32 v148, v199
	v_cvt_pk_fp8_f32 v148, v149, v150
	s_waitcnt vmcnt(13)
	v_mul_f32_e32 v149, v10, v146
	s_waitcnt vmcnt(12)
	v_mul_f32_e32 v150, v14, v146
	s_waitcnt vmcnt(10)
	v_mul_f32_e32 v151, v22, v146
	v_cvt_pk_fp8_f32 v148, v149, v150 op_sel:[0,0,1]
	v_mul_f32_e32 v150, v18, v146
	v_mov_b32_e32 v149, v199
	v_cvt_pk_fp8_f32 v149, v150, v151
	s_waitcnt vmcnt(9)
	v_mul_f32_e32 v150, v26, v146
	s_waitcnt vmcnt(8)
	v_mul_f32_e32 v151, v30, v146
	s_waitcnt vmcnt(6)
	v_mul_f32_e32 v152, v50, v146
	v_cvt_pk_fp8_f32 v149, v150, v151 op_sel:[0,0,1]
	v_mul_f32_e32 v151, v34, v146
	v_mov_b32_e32 v150, v199
	v_cvt_pk_fp8_f32 v150, v151, v152
	s_waitcnt vmcnt(5)
	v_mul_f32_e32 v151, v62, v146
	s_waitcnt vmcnt(4)
	v_mul_f32_e32 v152, v70, v146
	s_waitcnt vmcnt(2)
	v_mul_f32_e32 v153, v86, v146
	v_cvt_pk_fp8_f32 v150, v151, v152 op_sel:[0,0,1]
	v_mul_f32_e32 v152, v82, v146
	v_mov_b32_e32 v151, v199
	v_cvt_pk_fp8_f32 v151, v152, v153
	s_waitcnt vmcnt(1)
	v_mul_f32_e32 v152, v94, v146
	s_waitcnt vmcnt(0)
	v_mul_f32_e32 v153, v146, v102
	s_movk_i32 s7, 0xff80
	v_cvt_pk_fp8_f32 v151, v152, v153 op_sel:[0,0,1]
	v_mul_f32_e32 v152, v51, v146
	v_mul_f32_e32 v153, v87, v146
	s_ashr_i32 s43, s42, 31
	ds_write_b128 v141, v[148:151]
	v_mul_f32_e32 v149, v3, v146
	v_mul_f32_e32 v150, v7, v146
	v_mov_b32_e32 v148, v199
	v_cvt_pk_fp8_f32 v148, v149, v150
	v_mul_f32_e32 v149, v11, v146
	v_mul_f32_e32 v150, v15, v146
	v_mul_f32_e32 v151, v23, v146
	v_cvt_pk_fp8_f32 v148, v149, v150 op_sel:[0,0,1]
	v_mul_f32_e32 v150, v19, v146
	v_mov_b32_e32 v149, v199
	v_cvt_pk_fp8_f32 v149, v150, v151
	v_mul_f32_e32 v150, v27, v146
	v_mul_f32_e32 v151, v31, v146
	s_andn2_b64 vcc, exec, s[26:27]
	v_cvt_pk_fp8_f32 v149, v150, v151 op_sel:[0,0,1]
	v_mul_f32_e32 v151, v35, v146
	v_mov_b32_e32 v150, v199
	v_cvt_pk_fp8_f32 v150, v151, v152
	v_mul_f32_e32 v151, v63, v146
	v_mul_f32_e32 v152, v71, v146
	v_cvt_pk_fp8_f32 v150, v151, v152 op_sel:[0,0,1]
	v_mul_f32_e32 v152, v83, v146
	v_mov_b32_e32 v151, v199
	v_cvt_pk_fp8_f32 v151, v152, v153
	v_mul_f32_e32 v152, v95, v146
	v_mul_f32_e32 v153, v146, v103
	v_cvt_pk_fp8_f32 v151, v152, v153 op_sel:[0,0,1]
	v_mul_f32_e32 v152, v52, v146
	v_mul_f32_e32 v153, v88, v146
	ds_write_b128 v141, v[148:151] offset:8704
	v_mul_f32_e32 v149, v4, v146
	v_mul_f32_e32 v150, v8, v146
	v_mov_b32_e32 v148, v199
	v_cvt_pk_fp8_f32 v148, v149, v150
	v_mul_f32_e32 v149, v12, v146
	v_mul_f32_e32 v150, v16, v146
	v_mul_f32_e32 v151, v24, v146
	v_cvt_pk_fp8_f32 v148, v149, v150 op_sel:[0,0,1]
	v_mul_f32_e32 v150, v20, v146
	v_mov_b32_e32 v149, v199
	v_cvt_pk_fp8_f32 v149, v150, v151
	v_mul_f32_e32 v150, v28, v146
	v_mul_f32_e32 v151, v32, v146
	v_cvt_pk_fp8_f32 v149, v150, v151 op_sel:[0,0,1]
	v_mul_f32_e32 v151, v36, v146
	v_mov_b32_e32 v150, v199
	v_cvt_pk_fp8_f32 v150, v151, v152
	v_mul_f32_e32 v151, v64, v146
	v_mul_f32_e32 v152, v72, v146
	v_cvt_pk_fp8_f32 v150, v151, v152 op_sel:[0,0,1]
	v_mul_f32_e32 v152, v84, v146
	v_mov_b32_e32 v151, v199
	v_cvt_pk_fp8_f32 v151, v152, v153
	v_mul_f32_e32 v152, v96, v146
	v_mul_f32_e32 v153, v146, v104
	v_cvt_pk_fp8_f32 v151, v152, v153 op_sel:[0,0,1]
	v_mul_f32_e32 v152, v53, v146
	v_mul_f32_e32 v153, v89, v146
	ds_write_b128 v141, v[148:151] offset:17408
	v_mul_f32_e32 v149, v5, v146
	v_mul_f32_e32 v150, v9, v146
	v_mov_b32_e32 v148, v199
	v_cvt_pk_fp8_f32 v148, v149, v150
	v_mul_f32_e32 v149, v13, v146
	v_mul_f32_e32 v150, v17, v146
	v_mul_f32_e32 v151, v25, v146
	v_cvt_pk_fp8_f32 v148, v149, v150 op_sel:[0,0,1]
	v_mul_f32_e32 v150, v21, v146
	v_mov_b32_e32 v149, v199
	v_cvt_pk_fp8_f32 v149, v150, v151
	v_mul_f32_e32 v150, v29, v146
	v_mul_f32_e32 v151, v33, v146
	v_cvt_pk_fp8_f32 v149, v150, v151 op_sel:[0,0,1]
	v_mul_f32_e32 v151, v37, v146
	v_mov_b32_e32 v150, v199
	v_cvt_pk_fp8_f32 v150, v151, v152
	v_mul_f32_e32 v151, v65, v146
	v_mul_f32_e32 v152, v73, v146
	v_cvt_pk_fp8_f32 v150, v151, v152 op_sel:[0,0,1]
	v_mul_f32_e32 v152, v85, v146
	v_mov_b32_e32 v151, v199
	v_cvt_pk_fp8_f32 v151, v152, v153
	v_mul_f32_e32 v152, v97, v146
	v_mul_f32_e32 v153, v146, v105
	v_cvt_pk_fp8_f32 v151, v152, v153 op_sel:[0,0,1]
	v_add_u32_e32 v152, s44, v131
	v_lshlrev_b32_e32 v153, 1, v152
	v_ashrrev_i32_e32 v152, 3, v152
	v_and_b32_e32 v153, 0x700, v153
	v_and_or_b32 v152, v152, s7, v137
	v_add_u32_e32 v152, v152, v153
	ds_write_b128 v141, v[148:151] offset:26112
	s_waitcnt lgkmcnt(0)
	s_barrier
	ds_read_b128 v[148:151], v142
	v_ashrrev_i32_e32 v153, 31, v152
	v_lshlrev_b64 v[152:153], 10, v[152:153]
	v_lshl_add_u64 v[152:153], s[14:15], 0, v[152:153]
	v_lshl_add_u64 v[152:153], v[152:153], 0, s[42:43]
	v_lshl_add_u64 v[152:153], v[152:153], 0, v[132:133]
	s_waitcnt lgkmcnt(0)
	global_store_dwordx4 v[152:153], v[148:151], off
	v_add_u32_e32 v152, s44, v134
	v_lshlrev_b32_e32 v153, 1, v152
	v_ashrrev_i32_e32 v152, 3, v152
	v_and_b32_e32 v153, 0x700, v153
	v_and_or_b32 v152, v152, s7, v138
	v_add_u32_e32 v152, v152, v153
	ds_read_b128 v[148:151], v143
	v_ashrrev_i32_e32 v153, 31, v152
	v_lshlrev_b64 v[152:153], 10, v[152:153]
	v_lshl_add_u64 v[152:153], s[14:15], 0, v[152:153]
	v_lshl_add_u64 v[152:153], v[152:153], 0, s[42:43]
	v_lshl_add_u64 v[152:153], v[152:153], 0, v[132:133]
	s_waitcnt lgkmcnt(0)
	global_store_dwordx4 v[152:153], v[148:151], off
	v_add_u32_e32 v152, s44, v135
	v_lshlrev_b32_e32 v153, 1, v152
	v_ashrrev_i32_e32 v152, 3, v152
	v_and_b32_e32 v153, 0x700, v153
	v_and_or_b32 v152, v152, s7, v139
	v_add_u32_e32 v152, v152, v153
	ds_read_b128 v[148:151], v144
	v_ashrrev_i32_e32 v153, 31, v152
	v_lshlrev_b64 v[152:153], 10, v[152:153]
	v_lshl_add_u64 v[152:153], s[14:15], 0, v[152:153]
	v_lshl_add_u64 v[152:153], v[152:153], 0, s[42:43]
	v_lshl_add_u64 v[152:153], v[152:153], 0, v[132:133]
	s_waitcnt lgkmcnt(0)
	global_store_dwordx4 v[152:153], v[148:151], off
	v_add_u32_e32 v152, s44, v136
	v_lshlrev_b32_e32 v153, 1, v152
	v_ashrrev_i32_e32 v152, 3, v152
	v_and_b32_e32 v153, 0x700, v153
	v_and_or_b32 v152, v152, s7, v140
	v_add_u32_e32 v152, v152, v153
	ds_read_b128 v[148:151], v145
	v_ashrrev_i32_e32 v153, 31, v152
	v_lshlrev_b64 v[152:153], 10, v[152:153]
	v_lshl_add_u64 v[152:153], s[14:15], 0, v[152:153]
	v_lshl_add_u64 v[152:153], v[152:153], 0, s[42:43]
	v_lshl_add_u64 v[152:153], v[152:153], 0, v[132:133]
	s_waitcnt lgkmcnt(0)
	global_store_dwordx4 v[152:153], v[148:151], off
	s_cbranch_vccnz .LBB0_1353
; __device__ __forceinline__ float w_qscale(float wmax) { return exp2f(floorf(log2f(128.f / fmaxf(wmax, 1e-30f)))); }
; __device__ __forceinline__ bool witem_decode(const Frame& F, int l, int it, WItem& t) {
;     ...
;     if (r < N_GU) { const int le = l * NE + r / I_GU; t.W = F.in[16] + (size_t)le * D * 2048; t.WT = (unsigned char*)(F.ws + WS_WGU) + (size_t)le * 2048 * D; t.N = 2048; t.map = 1; nblk = 16; item = r % I_GU; t.scale = w_qscale(wmax[l * 2 + 0]); }
;     else if ((r -= N_GU) < N_DN) { const int le = l * NE + r / I_DN; t.W = F.in[18] + (size_t)le * FF * D; t.WT = (unsigned char*)(F.ws + WS_WDN) + (size_t)le * D * FF; t.N = D; t.map = 3; nblk = 8; item = r % I_DN; t.scale = w_qscale(wmax[l * 2 + 1]); }
;     else return false;
;     t.k0 = 256 * (item / nblk); t.n0 = 128 * (item % nblk); return true;
; }
; __device__ __forceinline__ void witem_load(const WItem& t, int wave, int lane, f32x4 (&v)[16]) {
;     const float* wp = t.W + (size_t)(t.k0 + 32 * wave + 16 * (lane >> 5)) * t.N + t.n0 + 4 * (lane & 31);
; #pragma unroll
;     for (int q = 0; q < 16; ++q) v[q] = __builtin_nontemporal_load((const f32x4*)(wp + (size_t)q * t.N));
; __device__ __forceinline__ void fp8_convert_range(const Frame& F, int l, int start, int stride, int limit) {
;     ...
;         const bool hb = it + stride < limit && witem_decode(F, l, it + stride, tb);
;         if (hb) witem_load(tb, F.wave, F.lane, vb);
	s_lshl_b32 s7, s74, 1
	s_add_i32 s6, s6, s7
	s_cmp_ge_i32 s6, s100
	s_cselect_b64 s[26:27], -1, 0
	s_and_b64 vcc, exec, s[26:27]
	s_cbranch_vccnz .LBB0_1347
	global_load_dword v2, v199, s[0:1]
	s_ashr_i32 s7, s6, 31
	s_lshr_b32 s7, s7, 26
	s_add_i32 s7, s6, s7
	s_ashr_i32 s8, s7, 6
	s_add_i32 s8, s8, s4
	s_ashr_i32 s9, s8, 31
	v_readlane_b32 s44, v249, 8
	s_lshl_b64 s[10:11], s[8:9], 23
	v_readlane_b32 s46, v249, 10
	v_readlane_b32 s47, v249, 11
	s_add_u32 s46, s46, s10
	s_addc_u32 s47, s47, s11
	s_lshl_b64 s[8:9], s[8:9], 21
	s_add_u32 s14, s3, s8
	s_mov_b32 s10, 0x43000000
	s_addc_u32 s15, s5, s9
	s_and_b32 s7, s7, 0xffc0
	s_sub_i32 s7, s6, s7
	v_readlane_b32 s45, v249, 9
	v_lshlrev_b32_e32 v198, 2, v130
	v_readlane_b32 s48, v249, 12
	v_readlane_b32 s49, v249, 13
	v_readlane_b32 s50, v249, 14
	v_readlane_b32 s51, v249, 15
	s_waitcnt vmcnt(0)
	v_max_f32_e32 v2, v2, v2
	v_max_f32_e32 v2, 0xda24260, v2
	v_div_scale_f32 v3, s[8:9], v2, v2, s10
	v_rcp_f32_e32 v4, v3
	s_mov_b32 s8, 0x800000
	v_fma_f32 v5, -v3, v4, 1.0
	v_fmac_f32_e32 v4, v5, v4
	v_div_scale_f32 v5, vcc, s10, v2, s10
	v_mul_f32_e32 v6, v5, v4
	v_fma_f32 v7, -v3, v6, v5
	v_fmac_f32_e32 v6, v7, v4
	v_fma_f32 v3, -v3, v6, v5
	v_div_fmas_f32 v3, v3, v4, v6
	v_div_fixup_f32 v2, v3, v2, s10
	v_cmp_gt_f32_e32 vcc, s8, v2
	s_and_b64 s[8:9], vcc, exec
	s_cselect_b32 s8, 32, 0
	v_ldexp_f32 v2, v2, s8
	v_log_f32_e32 v2, v2
	v_cndmask_b32_e32 v3, 0, v232, vcc
	s_mov_b32 s8, 0xc2fc0000
	v_sub_f32_e32 v2, v2, v3
	v_floor_f32_e32 v2, v2
	v_cmp_gt_f32_e32 vcc, s8, v2
	s_and_b64 s[8:9], vcc, exec
	s_cselect_b32 s8, 0xffffffc0, 0
	v_cndmask_b32_e32 v3, 0, v233, vcc
	v_add_f32_e32 v2, v2, v3
	v_exp_f32_e32 v2, v2
	s_nop 0
	v_ldexp_f32 v146, v2, s8
	s_bfe_i32 s8, s7, 0x80000
	s_bfe_u32 s8, s8, 0x4000b
	s_add_i32 s8, s7, s8
	s_bfe_i32 s9, s8, 0x80000
	s_sext_i32_i16 s9, s9
	s_lshl_b32 s9, s9, 4
	s_and_b32 s42, s9, 0xffffff00
	s_and_b32 s8, s8, 0xf0
	s_sub_i32 s7, s7, s8
	v_add_u32_e32 v2, s42, v1
	s_sext_i32_i8 s7, s7
	v_ashrrev_i32_e32 v3, 31, v2
	s_lshl_b32 s44, s7, 7
	v_lshlrev_b64 v[2:3], 13, v[2:3]
	v_lshl_add_u64 v[2:3], s[46:47], 0, v[2:3]
	s_ashr_i32 s45, s44, 31
	v_lshl_add_u64 v[2:3], s[44:45], 2, v[2:3]
	v_lshl_add_u64 v[102:103], v[2:3], 0, v[198:199]
	v_add_co_u32_e32 v6, vcc, s70, v102
	s_movk_i32 s7, 0x4000
	s_nop 0
	v_addc_co_u32_e32 v7, vcc, 0, v103, vcc
	v_add_co_u32_e32 v10, vcc, s7, v102
	s_movk_i32 s7, 0x6000
	s_nop 0
	v_addc_co_u32_e32 v11, vcc, 0, v103, vcc
	v_add_co_u32_e32 v14, vcc, s7, v102
	s_mov_b32 s7, 0x8000
	s_nop 0
	v_addc_co_u32_e32 v15, vcc, 0, v103, vcc
	v_add_co_u32_e32 v18, vcc, s7, v102
	s_mov_b32 s7, 0xa000
	s_nop 0
	v_addc_co_u32_e32 v19, vcc, 0, v103, vcc
	v_add_co_u32_e32 v22, vcc, s7, v102
	s_mov_b32 s7, 0xc000
	s_nop 0
	v_addc_co_u32_e32 v23, vcc, 0, v103, vcc
	v_add_co_u32_e32 v26, vcc, s7, v102
	s_mov_b32 s7, 0xe000
	s_nop 0
	v_addc_co_u32_e32 v27, vcc, 0, v103, vcc
	v_add_co_u32_e32 v30, vcc, s7, v102
	s_mov_b32 s7, 0x12000
	s_nop 0
	v_addc_co_u32_e32 v31, vcc, 0, v103, vcc
	v_add_co_u32_e32 v34, vcc, s71, v102
	global_load_dwordx4 v[2:5], v[102:103], off nt
	s_nop 0
	v_addc_co_u32_e32 v35, vcc, 0, v103, vcc
	v_add_co_u32_e32 v50, vcc, s7, v102
	s_mov_b32 s7, 0x14000
	s_nop 0
	v_addc_co_u32_e32 v51, vcc, 0, v103, vcc
	v_add_co_u32_e32 v62, vcc, s7, v102
	s_mov_b32 s7, 0x16000
	s_nop 0
	v_addc_co_u32_e32 v63, vcc, 0, v103, vcc
	v_add_co_u32_e32 v70, vcc, s7, v102
	s_mov_b32 s7, 0x18000
	s_nop 0
	v_addc_co_u32_e32 v71, vcc, 0, v103, vcc
	v_add_co_u32_e32 v82, vcc, s7, v102
	global_load_dwordx4 v[6:9], v[6:7], off nt
	s_nop 0
	v_addc_co_u32_e32 v83, vcc, 0, v103, vcc
	v_add_co_u32_e32 v86, vcc, 0x1a000, v102
	global_load_dwordx4 v[10:13], v[10:11], off nt
	s_nop 0
	v_addc_co_u32_e32 v87, vcc, 0, v103, vcc
	v_add_co_u32_e32 v94, vcc, 0x1c000, v102
	global_load_dwordx4 v[14:17], v[14:15], off nt
	s_nop 0
	v_addc_co_u32_e32 v95, vcc, 0, v103, vcc
	v_add_co_u32_e32 v102, vcc, 0x1e000, v102
	global_load_dwordx4 v[18:21], v[18:19], off nt
	s_nop 0
	v_addc_co_u32_e32 v103, vcc, 0, v103, vcc
	global_load_dwordx4 v[22:25], v[22:23], off nt
	s_nop 0
	global_load_dwordx4 v[26:29], v[26:27], off nt
	s_nop 0
	global_load_dwordx4 v[30:33], v[30:31], off nt
	s_nop 0
	global_load_dwordx4 v[34:37], v[34:35], off nt
	s_nop 0
	global_load_dwordx4 v[50:53], v[50:51], off nt
	s_nop 0
	global_load_dwordx4 v[62:65], v[62:63], off nt
	s_nop 0
	global_load_dwordx4 v[70:73], v[70:71], off nt
	s_nop 0
	global_load_dwordx4 v[82:85], v[82:83], off nt
	s_nop 0
	global_load_dwordx4 v[86:89], v[86:87], off nt
	s_nop 0
	global_load_dwordx4 v[94:97], v[94:95], off nt
	s_nop 0
	global_load_dwordx4 v[102:105], v[102:103], off nt
	s_branch .LBB0_1347

; __device__ __forceinline__ void fp8_convert_range(const Frame& F, int l, int start, int stride, int limit) {
;     ...
;     }
;     __syncthreads();
.LBB0_1354:
	s_barrier
	s_cmp_lg_u32 s101, 0
	s_cbranch_scc1 .Ltc_ret

; #define SEAM(k) do { if (IN(k) && IN((k) + 1)) xcd_barrier(bar, is_t0); } while (0)
; __device__ __forceinline__ void fp8_convert_range(const Frame& F, int l, int start, int stride, int limit) {
;     __syncthreads();
;     WItem ta, tb; f32x4 va[16], vb[16];
;     int it = start;
;     bool ha = it < limit && witem_decode(F, l, it, ta);
;     if (ha) witem_load(ta, F.wave, F.lane, va);
; __global__ void __launch_bounds__(NTHR, 2) fwd(Args args) {
;     ...
;         if ((PMASK & 256) && IN(pb + 6)) { for (int rep = 0; rep < REPS(256); ++rep) { F = launder(F); phase_moe<1>(F, l); if (REPS(256) > 1) __syncthreads(); } SEAM(pb + 6); }
.LBB0_2367:
	s_cmp_lt_u32 s80, 128
	s_cbranch_scc1 .Ltc_skip
	s_cmp_gt_u32 s96, 2
	s_cbranch_scc1 .Ltc_skip
	s_sub_i32 s0, s80, 128
	s_lshr_b32 s1, s0, 6
	s_and_b32 s3, s0, 63
	s_lshr_b32 s4, s3, 4
	s_lshl_b32 s4, s4, 8
	s_and_b32 s3, s3, 15
	s_lshl_b32 s3, s3, 7
	s_mov_b32 s5, 0
	v_writelane_b32 v248, s1, 41
	v_writelane_b32 v248, s0, 42
	v_writelane_b32 v248, s4, 43
	v_writelane_b32 v248, s3, 44
	v_writelane_b32 v248, s5, 45
	s_add_i32 s96, s96, 1
	s_lshl_b32 s28, s96, 1
	s_mov_b32 s29, 0
	s_movk_i32 s74, 0x80
	s_movk_i32 s70, 0x2000
	s_mov_b32 s71, 0x10000
	v_readfirstlane_b32 s8, v0
	s_ashr_i32 s8, s8, 6
	v_and_b32_e32 v66, 63, v0
	v_lshlrev_b32_e32 v66, 2, v66
	s_movk_i32 s100, 0x180
	s_mov_b32 s101, 1
	s_mov_b64 exec, -1
	s_branch .Lcvt_entry
.Ltc_ret:
	s_mov_b32 s101, 0
	s_sub_i32 s96, s96, 1
	v_readlane_b32 s28, v249, 44
	v_readlane_b32 s29, v249, 45
	v_readlane_b32 s74, v249, 46
	s_movk_i32 s70, 0x2000
	s_mov_b32 s71, 0x10000
	v_readlane_b32 s0, v250, 56
	v_readlane_b32 s1, v250, 57
	s_nop 1
	v_cndmask_b32_e64 v1, 0, 1, s[0:1]
	v_cmp_ne_u32_e64 s[36:37], 1, v1
